# attn1_ssd1_n1
# speedup vs baseline: 1.0010x; 1.0010x over previous
.LBB0_875:
	s_movk_i32 s4, 0x3fff
	v_cmp_lt_i32_e32 vcc, s4, v30
	s_and_saveexec_b64 s[4:5], vcc
	s_xor_b64 s[12:13], exec, s[4:5]
	s_cbranch_execz .LBB0_881
	v_and_b32_e32 v0, 0x7ffffe00, v30
	s_movk_i32 s4, 0x4000
	v_cmp_ne_u32_e32 vcc, s4, v0
	v_mov_b32_e32 v3, s55
	v_mov_b32_e32 v4, s53
	v_cmp_eq_u32_e64 s[4:5], s4, v0
	v_mov_b32_e32 v0, s54
	v_bfe_u32 v2, v30, 8, 1
	v_cndmask_b32_e64 v5, v3, v4, s[4:5]
	v_mov_b32_e32 v3, s52
	v_cndmask_b32_e64 v4, v0, v3, s[4:5]
	v_readlane_b32 s4, v255, 27
	v_lshlrev_b32_sdwa v0, v196, v30 dst_sel:DWORD dst_unused:UNUSED_PAD src0_sel:DWORD src1_sel:BYTE_0
	v_readlane_b32 s5, v255, 28
	v_lshl_add_u32 v6, v2, 2, s4
	v_ashrrev_i32_e32 v7, 31, v6
	v_lshlrev_b64 v[6:7], 20, v[6:7]
	v_lshl_add_u64 v[4:5], v[4:5], 0, v[6:7]
	v_lshl_add_u64 v[4:5], v[4:5], 0, v[0:1]
	s_and_saveexec_b64 s[4:5], vcc
	s_xor_b64 s[4:5], exec, s[4:5]
	s_cbranch_execz .LBB0_878
	v_mul_u32_u24_e32 v0, 0x440000, v2
	v_readlane_b32 s14, v254, 4
	v_lshlrev_b32_e32 v0, 1, v0
	v_readlane_b32 s15, v254, 5
	v_mov_b32_e32 v85, v1
	v_lshl_add_u64 v[4:5], v[4:5], 0, v[84:85]
	v_lshl_add_u64 v[2:3], s[14:15], 0, v[0:1]
	v_mov_b32_e32 v0, 1
	v_lshlrev_b32_sdwa v0, v0, v30 dst_sel:DWORD dst_unused:UNUSED_PAD src0_sel:DWORD src1_sel:BYTE_0
	v_lshl_add_u64 v[2:3], v[2:3], 0, v[0:1]
	global_load_dword v8, v[4:5], off
	global_load_dword v9, v[4:5], off offset:256
	global_load_dword v10, v[4:5], off offset:512
	global_load_dword v11, v[4:5], off offset:768
	global_load_dword v12, v[4:5], off offset:1024
	global_load_dword v13, v[4:5], off offset:1280
	global_load_dword v14, v[4:5], off offset:1536
	global_load_dword v15, v[4:5], off offset:1792
	global_load_dword v16, v[4:5], off offset:2048
	global_load_dword v17, v[4:5], off offset:2304
	global_load_dword v18, v[4:5], off offset:2560
	global_load_dword v19, v[4:5], off offset:2816
	global_load_dword v20, v[4:5], off offset:3072
	global_load_dword v21, v[4:5], off offset:3328
	global_load_dword v22, v[4:5], off offset:3584
	global_load_dword v23, v[4:5], off offset:3840
	s_waitcnt vmcnt(0)
	v_lshl_add_u64 v[6:7], v[2:3], 0, v[34:35]
	v_cvt_pk_bf16_f32 v0, v8, s0
	global_store_short v[6:7], v0, off
	v_lshl_add_u64 v[6:7], v[2:3], 0, v[36:37]
	v_cvt_pk_bf16_f32 v0, v9, s0
	global_store_short v[6:7], v0, off
	v_lshl_add_u64 v[6:7], v[2:3], 0, v[38:39]
	v_cvt_pk_bf16_f32 v0, v10, s0
	global_store_short v[6:7], v0, off
	v_lshl_add_u64 v[6:7], v[2:3], 0, v[40:41]
	v_cvt_pk_bf16_f32 v0, v11, s0
	global_store_short v[6:7], v0, off
	v_lshl_add_u64 v[6:7], v[2:3], 0, v[42:43]
	v_cvt_pk_bf16_f32 v0, v12, s0
	global_store_short v[6:7], v0, off
	v_lshl_add_u64 v[6:7], v[2:3], 0, v[44:45]
	v_cvt_pk_bf16_f32 v0, v13, s0
	global_store_short v[6:7], v0, off
	v_lshl_add_u64 v[6:7], v[2:3], 0, v[46:47]
	v_cvt_pk_bf16_f32 v0, v14, s0
	global_store_short v[6:7], v0, off
	v_lshl_add_u64 v[6:7], v[2:3], 0, v[48:49]
	v_cvt_pk_bf16_f32 v0, v15, s0
	global_store_short v[6:7], v0, off
	v_lshl_add_u64 v[6:7], v[2:3], 0, v[50:51]
	v_cvt_pk_bf16_f32 v0, v16, s0
	global_store_short v[6:7], v0, off
	v_lshl_add_u64 v[6:7], v[2:3], 0, v[52:53]
	v_cvt_pk_bf16_f32 v0, v17, s0
	global_store_short v[6:7], v0, off
	v_lshl_add_u64 v[6:7], v[2:3], 0, v[54:55]
	v_cvt_pk_bf16_f32 v0, v18, s0
	global_store_short v[6:7], v0, off
	v_lshl_add_u64 v[6:7], v[2:3], 0, v[56:57]
	v_cvt_pk_bf16_f32 v0, v19, s0
	global_store_short v[6:7], v0, off
	v_lshl_add_u64 v[6:7], v[2:3], 0, v[58:59]
	v_cvt_pk_bf16_f32 v0, v20, s0
	global_store_short v[6:7], v0, off
	v_lshl_add_u64 v[6:7], v[2:3], 0, v[60:61]
	v_cvt_pk_bf16_f32 v0, v21, s0
	global_store_short v[6:7], v0, off
	v_lshl_add_u64 v[6:7], v[2:3], 0, v[62:63]
	v_cvt_pk_bf16_f32 v0, v22, s0
	global_store_short v[6:7], v0, off
	v_lshl_add_u64 v[2:3], v[2:3], 0, v[64:65]
	v_cvt_pk_bf16_f32 v0, v23, s0
	global_store_short v[2:3], v0, off
.LBB0_878:
	s_andn2_saveexec_b64 s[4:5], s[4:5]
	s_cbranch_execz .LBB0_880
	v_mul_u32_u24_e32 v0, 0x1100, v2
	v_or_b32_sdwa v0, v0, v30 dst_sel:DWORD dst_unused:UNUSED_PAD src0_sel:DWORD src1_sel:BYTE_0
	v_lshlrev_b32_e32 v0, 11, v0
	v_lshl_add_u64 v[2:3], s[68:69], 0, v[0:1]
	v_lshlrev_b32_e32 v0, 2, v32
	s_mov_b64 s[14:15], 0x1fb24000
	v_lshl_add_u64 v[8:9], v[4:5], 0, v[0:1]
	v_lshl_add_u64 v[6:7], v[2:3], 0, s[14:15]
	global_load_dwordx4 v[10:13], v[8:9], off
	global_load_dwordx4 v[14:17], v[8:9], off offset:1024
	global_load_dwordx4 v[18:21], v[8:9], off offset:2048
	global_load_dwordx4 v[22:25], v[8:9], off offset:3072
	s_waitcnt vmcnt(0)
	v_lshlrev_b32_e32 v0, 1, v32
	v_cvt_pk_bf16_f32 v2, v10, v11
	v_cvt_pk_bf16_f32 v3, v12, v13
	v_lshl_add_u64 v[4:5], v[6:7], 0, v[0:1]
	global_store_dwordx2 v[4:5], v[2:3], off
	v_lshlrev_b32_e32 v0, 1, v66
	v_cvt_pk_bf16_f32 v2, v14, v15
	v_cvt_pk_bf16_f32 v3, v16, v17
	v_lshl_add_u64 v[4:5], v[6:7], 0, v[0:1]
	global_store_dwordx2 v[4:5], v[2:3], off
	v_lshlrev_b32_e32 v0, 1, v68
	v_cvt_pk_bf16_f32 v2, v18, v19
	v_cvt_pk_bf16_f32 v3, v20, v21
	v_lshl_add_u64 v[4:5], v[6:7], 0, v[0:1]
	global_store_dwordx2 v[4:5], v[2:3], off
	v_lshlrev_b32_e32 v0, 1, v70
	v_cvt_pk_bf16_f32 v2, v22, v23
	v_cvt_pk_bf16_f32 v3, v24, v25
	v_lshl_add_u64 v[4:5], v[6:7], 0, v[0:1]
	global_store_dwordx2 v[4:5], v[2:3], off
